# speedup vs baseline: 1.0063x; 1.0063x over previous
; __device__ __forceinline__ int tidx() { int t = threadIdx.x; asm volatile("" : "+v"(t)); return t; }
; template <int NT, bool LOWREG = false>
; __device__ __forceinline__ void gemm_mainloop(const bh* __restrict__ A, long lda, const bh* __restrict__ B, long ldb, int K,
;                                               char* lds, f32x4 (&acc)[4][NT]) {
;     ...
;   const int tid = tidx(), lane = tid & 63, wid = tid >> 6, wr = wid >> 1, wc = wid & 1, fr = lane & 15, fq = lane >> 4;
;   const int srow = tid >> 3, scol = (tid & 7) * 8;
;   const bh* Ap = A + (long)srow * lda + scol;
;   const bh* Bp = B + (long)srow * ldb + scol;
;   bf16x8 ra[4], rb[NB];
;   const int nk = K >> 6;
; #pragma unroll
;   for (int i = 0; i < 4; ++i) ra[i] = *reinterpret_cast<const bf16x8*>(Ap + (long)(64 * i) * lda);
; #pragma unroll
;   for (int i = 0; i < NB; ++i) rb[i] = *reinterpret_cast<const bf16x8*>(Bp + (long)(64 * i) * ldb);
; #pragma unroll
;   for (int i = 0; i < 4; ++i) *reinterpret_cast<bf16x8*>(lds + (srow + 64 * i) * LROW + scol * 2) = ra[i];
; #pragma unroll
;   for (int i = 0; i < NB; ++i) *reinterpret_cast<bf16x8*>(lds + A_BYTES + (srow + 64 * i) * LROW + scol * 2) = rb[i];
;   __syncthreads();
; #pragma unroll 1
;   for (int kt = 0; kt < nk; ++kt) {
;     const bool more = kt + 1 < nk;
;     if (more) {
; #pragma unroll
;       for (int i = 0; i < 4; ++i) ra[i] = *reinterpret_cast<const bf16x8*>(Ap + (long)(64 * i) * lda + (kt + 1) * 64);
; #pragma unroll
;       for (int i = 0; i < NB; ++i) rb[i] = *reinterpret_cast<const bf16x8*>(Bp + (long)(64 * i) * ldb + (kt + 1) * 64);
;     }
;     ...
;   for (int tile = (t_first >= 0 ? t_first : (int)blockIdx.x); tile < tm_n * tn_n; tile += (t_first >= 0 ? t_stride : (int)gridDim.x)) {
;     const int tn = tile / tm_n, tm = tile - tn * tm_n;
;     f32x4 acc[4][NT];
; #pragma unroll
;     for (int m = 0; m < 4; ++m)
; #pragma unroll
;       for (int n = 0; n < NT; ++n) acc[m][n] = f32x4{0.f, 0.f, 0.f, 0.f};
;     gemm_mainloop<NT>(A + (long)tm * 256 * lda, lda, Bt + (long)tn * BN * ldb, ldb, K, lds, acc);
.LBB0_207:
	s_ashr_i32 s3, s2, 31
	s_lshl_b64 s[10:11], s[2:3], 19
	s_lshr_b32 s3, s3, 26
	s_add_i32 s3, s2, s3
	s_and_b32 s4, s3, 0xffffffc0
	s_sub_i32 s6, s2, s4
	s_ashr_i32 s7, s6, 31
	s_waitcnt vmcnt(9)
	v_mov_b32_e32 v27, v188
	s_ashr_i32 s8, s3, 6
	s_lshl_b64 s[12:13], s[6:7], 19
	s_add_u32 s16, s38, s12
	v_ashrrev_i32_e32 v40, 3, v27
	v_ashrrev_i32_e32 v41, 31, v40
	s_addc_u32 s17, s39, s13
	v_lshlrev_b64 v[42:43], 11, v[40:41]
	v_lshlrev_b32_e32 v2, 4, v27
	v_lshl_add_u64 v[0:1], s[16:17], 0, v[42:43]
	v_and_b32_e32 v176, 0x70, v2
	v_lshl_add_u64 v[0:1], v[0:1], 0, v[176:177]
	s_mov_b32 s3, 0x20000
	v_add_co_u32_e32 v4, vcc, s3, v0
	s_ashr_i32 s9, s8, 31
	s_nop 0
	v_addc_co_u32_e32 v5, vcc, 0, v1, vcc
	s_mov_b32 s3, 0x40000
	s_lshl_b64 s[12:13], s[8:9], 17
	global_load_dwordx4 v[16:19], v[0:1], off
	global_load_dwordx4 v[20:23], v[4:5], off
	v_add_co_u32_e32 v4, vcc, s3, v0
	s_add_u32 s8, s14, s12
	s_nop 0
	v_addc_co_u32_e32 v5, vcc, 0, v1, vcc
	s_mov_b32 s3, 0x60000
	s_addc_u32 s9, s15, s13
	v_add_co_u32_e32 v0, vcc, s3, v0
	v_lshl_add_u64 v[2:3], s[8:9], 0, v[42:43]
	s_nop 0
	v_addc_co_u32_e32 v1, vcc, 0, v1, vcc
	global_load_dwordx4 v[28:31], v[4:5], off
	global_load_dwordx4 v[32:35], v[0:1], off
	v_lshl_add_u64 v[0:1], v[2:3], 0, v[176:177]
	global_load_dwordx4 v[36:39], v[0:1], off
	v_and_b32_e32 v41, 15, v27
	v_and_b32_e32 v58, 48, v27
	v_lshrrev_b32_e32 v27, 1, v27
	s_mov_b32 s5, 0x7ffffc0
	v_mul_lo_u32 v59, v40, s73
	v_and_or_b32 v40, v27, s5, v41
	v_and_or_b32 v27, v27, 32, v41
	v_mul_lo_u32 v60, v40, s73
	v_lshl_add_u64 v[40:41], s[10:11], 0, v[42:43]
	v_lshl_add_u64 v[42:43], s[12:13], 0, v[42:43]
	s_ashr_i32 s5, s4, 31
	v_mul_u32_u24_e32 v61, 0xa0, v27
	v_or_b32_e32 v27, v40, v176
	v_or_b32_e32 v42, v42, v176
	s_lshl_b64 s[10:11], s[4:5], 19
	v_lshl_add_u64 v[52:53], s[0:1], 0, v[42:43]
	v_mov_b32_e32 v42, s11
	v_subrev_co_u32_e32 v40, vcc, s10, v27
	v_mov_b32_e32 v0, 0
	v_add3_u32 v44, 32, v176, v59
	v_add3_u32 v45, 32, v59, v176
	v_subb_co_u32_e32 v41, vcc, v41, v42, vcc
	s_mov_b32 s3, 0
	s_mov_b64 s[8:9], 0
	v_mov_b32_e32 v1, v0
	v_mov_b32_e32 v2, v0
	v_mov_b32_e32 v3, v0
	v_mov_b32_e32 v4, v0
	v_mov_b32_e32 v5, v0
	v_mov_b32_e32 v6, v0
	v_mov_b32_e32 v7, v0
	v_mov_b32_e32 v8, v0
	v_mov_b32_e32 v9, v0
	v_mov_b32_e32 v10, v0
	v_mov_b32_e32 v11, v0
	v_mov_b32_e32 v12, v0
	v_mov_b32_e32 v13, v0
	v_mov_b32_e32 v14, v0
	v_mov_b32_e32 v15, v0
	v_mov_b32_e32 v24, v0
	v_mov_b32_e32 v25, v0
	v_mov_b32_e32 v26, v0
	v_lshl_add_u64 v[54:55], s[28:29], 0, v[40:41]
	v_mov_b32_e32 v27, v0
	v_mov_b32_e32 v40, v0
	v_mov_b32_e32 v41, v0
	v_mov_b32_e32 v42, v0
	v_mov_b32_e32 v43, v0
	v_mov_b32_e32 v46, v0
	v_mov_b32_e32 v47, v0
	s_waitcnt vmcnt(4)
	ds_write_b128 v44, v[16:19]
	s_waitcnt vmcnt(3)
	ds_write_b128 v44, v[20:23] offset:10240
	s_waitcnt vmcnt(2)
	ds_write_b128 v44, v[28:31] offset:20480
	s_waitcnt vmcnt(1)
	ds_write_b128 v44, v[32:35] offset:30720
	s_waitcnt vmcnt(0)
	ds_write_b128 v45, v[36:39] offset:40960
	v_mov_b32_e32 v44, v0
	v_mov_b32_e32 v45, v0
	v_mov_b32_e32 v48, v0
	v_mov_b32_e32 v49, v0
	v_mov_b32_e32 v50, v0
	v_mov_b32_e32 v51, v0
	v_lshl_add_u64 v[28:29], v[54:55], 0, s[8:9]
	v_add_co_u32_e32 v16, vcc, 0x5770000, v28
	v_lshl_add_u64 v[36:37], v[52:53], 0, s[8:9]
	v_addc_co_u32_e32 v17, vcc, 0, v29, vcc
	v_add_co_u32_e32 v20, vcc, 0x5790000, v28
	s_nop 1
	v_addc_co_u32_e32 v21, vcc, 0, v29, vcc
	v_add_co_u32_e32 v30, vcc, 0x57b0000, v28
	global_load_dwordx4 v[16:19], v[16:17], off offset:128
	s_nop 0
	global_load_dwordx4 v[20:23], v[20:21], off offset:128
	v_addc_co_u32_e32 v31, vcc, 0, v29, vcc
	v_add_co_u32_e32 v32, vcc, 0x57d0000, v28
	s_nop 1
	v_addc_co_u32_e32 v33, vcc, 0, v29, vcc
	global_load_dwordx4 v[28:31], v[30:31], off offset:128
	s_nop 0
	global_load_dwordx4 v[32:35], v[32:33], off offset:128
	s_nop 0
	global_load_dwordx4 v[36:39], v[36:37], off
	v_lshl_add_u64 v[104:105], v[54:55], 0, s[8:9]
	v_add_co_u32_e32 v92, vcc, 0x5770000, v104
	v_lshl_add_u64 v[160:161], v[52:53], 0, s[8:9]
	v_addc_co_u32_e32 v93, vcc, 0, v105, vcc
	v_add_co_u32_e32 v96, vcc, 0x5790000, v104
	s_nop 1
	v_addc_co_u32_e32 v97, vcc, 0, v105, vcc
	v_add_co_u32_e32 v106, vcc, 0x57b0000, v104
	global_load_dwordx4 v[92:95], v[92:93], off offset:256
	s_nop 0
	global_load_dwordx4 v[96:99], v[96:97], off offset:256
	v_addc_co_u32_e32 v107, vcc, 0, v105, vcc
	v_add_co_u32_e32 v108, vcc, 0x57d0000, v104
	s_nop 1
	v_addc_co_u32_e32 v109, vcc, 0, v105, vcc
	global_load_dwordx4 v[104:107], v[106:107], off offset:256
	s_nop 0
	global_load_dwordx4 v[108:111], v[108:109], off offset:256
	s_nop 0
	global_load_dwordx4 v[160:163], v[160:161], off offset:128
	s_waitcnt lgkmcnt(0)
	s_barrier
	s_branch .LBB0_209
; template <int NT, bool LOWREG = false>
; __device__ __forceinline__ void gemm_mainloop(const bh* __restrict__ A, long lda, const bh* __restrict__ B, long ldb, int K,
;                                               char* lds, f32x4 (&acc)[4][NT]) {
;     ...
;   for (int kt = 0; kt < nk; ++kt) {
;     const bool more = kt + 1 < nk;
;     if (more) {
; #pragma unroll
;       for (int i = 0; i < 4; ++i) ra[i] = *reinterpret_cast<const bf16x8*>(Ap + (long)(64 * i) * lda + (kt + 1) * 64);
; #pragma unroll
;       for (int i = 0; i < NB; ++i) rb[i] = *reinterpret_cast<const bf16x8*>(Bp + (long)(64 * i) * ldb + (kt + 1) * 64);
;     }
;     const char* sb = lds + (kt & 1) * STAGE;
;     const char* a_base = sb + (wr * 64 + fr) * LROW + fq * 16;
;     const char* b_base = sb + A_BYTES + (wc * (16 * NT) + fr) * LROW + fq * 16;
; #pragma unroll
;     for (int ks = 0; ks < 2; ++ks) {
;       if constexpr (LOWREG) {
;         bf16x8 bfr[NT];
; #pragma unroll
;         for (int n = 0; n < NT; ++n) bfr[n] = *reinterpret_cast<const bf16x8*>(b_base + n * 16 * LROW + ks * 64);
; #pragma unroll
;         for (int mp = 0; mp < 2; ++mp) {
;           bf16x8 af[2];
; #pragma unroll
;           for (int m = 0; m < 2; ++m) af[m] = *reinterpret_cast<const bf16x8*>(a_base + (mp * 2 + m) * 16 * LROW + ks * 64);
;           __builtin_amdgcn_s_setprio(1);
; #pragma unroll
;           for (int m = 0; m < 2; ++m)
; #pragma unroll
;             for (int n = 0; n < NT; ++n) acc[mp * 2 + m][n] = mfma16(af[m], bfr[n], acc[mp * 2 + m][n]);
;           __builtin_amdgcn_s_setprio(0);
;         }
;       } else {
;       bf16x8 af[4], bfr[NT];
; #pragma unroll
;       for (int m = 0; m < 4; ++m) af[m] = *reinterpret_cast<const bf16x8*>(a_base + m * 16 * LROW + ks * 64);
; #pragma unroll
;       for (int n = 0; n < NT; ++n) bfr[n] = *reinterpret_cast<const bf16x8*>(b_base + n * 16 * LROW + ks * 64);
;       __builtin_amdgcn_s_setprio(1);
; #pragma unroll
;       for (int m = 0; m < 4; ++m)
; #pragma unroll
;         for (int n = 0; n < NT; ++n) acc[m][n] = mfma16(af[m], bfr[n], acc[m][n]);
;       __builtin_amdgcn_s_setprio(0);
;       }
;     }
;     if (more) {
;       char* wb = lds + ((kt + 1) & 1) * STAGE;
; #pragma unroll
;       for (int i = 0; i < 4; ++i) *reinterpret_cast<bf16x8*>(wb + (srow + 64 * i) * LROW + scol * 2) = ra[i];
; #pragma unroll
.LBB0_208:
	s_add_u32 s8, s8, 0x80
	s_addc_u32 s9, s9, 0
	s_cmpk_ge_i32 s8, 0x700
	s_cbranch_scc1 .Lmy_2a_skipA_208
	v_lshl_add_u64 v[28:29], v[54:55], 0, s[8:9]
	v_add_co_u32_e32 v16, vcc, 0x5770000, v28
	v_lshl_add_u64 v[36:37], v[52:53], 0, s[8:9]
	v_addc_co_u32_e32 v17, vcc, 0, v29, vcc
	v_add_co_u32_e32 v20, vcc, 0x5790000, v28
	s_nop 1
	v_addc_co_u32_e32 v21, vcc, 0, v29, vcc
	v_add_co_u32_e32 v30, vcc, 0x57b0000, v28
	global_load_dwordx4 v[16:19], v[16:17], off offset:256
	s_nop 0
	global_load_dwordx4 v[20:23], v[20:21], off offset:256
	v_addc_co_u32_e32 v31, vcc, 0, v29, vcc
	v_add_co_u32_e32 v32, vcc, 0x57d0000, v28
	s_nop 1
	v_addc_co_u32_e32 v33, vcc, 0, v29, vcc
	global_load_dwordx4 v[28:31], v[30:31], off offset:256
	s_nop 0
	global_load_dwordx4 v[32:35], v[32:33], off offset:256
	s_nop 0
	global_load_dwordx4 v[36:39], v[36:37], off offset:128
.Lmy_2a_skipA_208:
	s_mov_b32 s3, s5
	s_waitcnt lgkmcnt(0)
	s_barrier
	s_add_i32 s5, s3, 1
	s_bitcmp1_b32 s3, 0
	s_cselect_b32 s3, 0xc800, 0
	s_add_i32 s3, s3, 32
	v_add3_u32 v86, s3, v60, v58
	v_add3_u32 v87, s3, v61, v58
	ds_read_b128 v[62:65], v86
	ds_read_b128 v[66:69], v86 offset:2560
	ds_read_b128 v[70:73], v86 offset:5120
	ds_read_b128 v[74:77], v86 offset:7680
	ds_read_b128 v[78:81], v87 offset:40960
	ds_read_b128 v[82:85], v87 offset:43520
	s_setprio 1
	s_waitcnt lgkmcnt(1)
	v_mfma_f32_16x16x32_bf16 v[48:51], v[62:65], v[78:81], v[48:51]
	s_waitcnt lgkmcnt(0)
	v_mfma_f32_16x16x32_bf16 v[44:47], v[62:65], v[82:85], v[44:47]
	v_mfma_f32_16x16x32_bf16 v[40:43], v[66:69], v[78:81], v[40:43]
	v_mfma_f32_16x16x32_bf16 v[24:27], v[66:69], v[82:85], v[24:27]
	v_mfma_f32_16x16x32_bf16 v[12:15], v[70:73], v[78:81], v[12:15]
	v_mfma_f32_16x16x32_bf16 v[8:11], v[70:73], v[82:85], v[8:11]
	v_mfma_f32_16x16x32_bf16 v[4:7], v[74:77], v[78:81], v[4:7]
	v_mfma_f32_16x16x32_bf16 v[0:3], v[74:77], v[82:85], v[0:3]
	s_setprio 0
	ds_read_b128 v[62:65], v86 offset:64
	ds_read_b128 v[66:69], v86 offset:2624
	ds_read_b128 v[70:73], v86 offset:5184
	ds_read_b128 v[74:77], v86 offset:7744
	ds_read_b128 v[78:81], v87 offset:41024
	ds_read_b128 v[82:85], v87 offset:43584
	s_cmpk_eq_i32 s8, 0x780
	s_cbranch_scc1 .Lmy_2a_lastB_208
	s_bitcmp1_b32 s5, 0
	s_cselect_b32 s3, 0xc800, 0
	s_add_i32 s3, s3, 32
	s_setprio 1
	s_waitcnt lgkmcnt(1)
	v_mfma_f32_16x16x32_bf16 v[48:51], v[62:65], v[78:81], v[48:51]
	s_waitcnt lgkmcnt(0)
	v_mfma_f32_16x16x32_bf16 v[44:47], v[62:65], v[82:85], v[44:47]
	v_mfma_f32_16x16x32_bf16 v[40:43], v[66:69], v[78:81], v[40:43]
	v_add3_u32 v62, s3, v176, v59
	s_waitcnt vmcnt(9)
	ds_write_b128 v62, v[92:95]
	v_mfma_f32_16x16x32_bf16 v[24:27], v[66:69], v[82:85], v[24:27]
	s_waitcnt vmcnt(8)
	ds_write_b128 v62, v[96:99] offset:10240
	v_mfma_f32_16x16x32_bf16 v[12:15], v[70:73], v[78:81], v[12:15]
	s_waitcnt vmcnt(7)
	ds_write_b128 v62, v[104:107] offset:20480
	v_mfma_f32_16x16x32_bf16 v[8:11], v[70:73], v[82:85], v[8:11]
	s_waitcnt vmcnt(6)
	ds_write_b128 v62, v[108:111] offset:30720
	v_mfma_f32_16x16x32_bf16 v[4:7], v[74:77], v[78:81], v[4:7]
	v_add3_u32 v62, s3, v59, v176
	s_waitcnt vmcnt(5)
	ds_write_b128 v62, v[160:163] offset:40960
	v_mfma_f32_16x16x32_bf16 v[0:3], v[74:77], v[82:85], v[0:3]
	s_setprio 0
	s_branch .Lmy_2a_latchB_208

; template <int NT, bool LOWREG = false>
; __device__ __forceinline__ void gemm_mainloop(const bh* __restrict__ A, long lda, const bh* __restrict__ B, long ldb, int K,
;                                               char* lds, f32x4 (&acc)[4][NT]) {
;     ...
;     if (more) {
; #pragma unroll
;       for (int i = 0; i < 4; ++i) ra[i] = *reinterpret_cast<const bf16x8*>(Ap + (long)(64 * i) * lda + (kt + 1) * 64);
; #pragma unroll
;       for (int i = 0; i < NB; ++i) rb[i] = *reinterpret_cast<const bf16x8*>(Bp + (long)(64 * i) * ldb + (kt + 1) * 64);
;     }
.Lmy_2a_latchB_208:
	s_add_u32 s8, s8, 0x80
	s_addc_u32 s9, s9, 0
	s_cmpk_ge_i32 s8, 0x700
	s_cbranch_scc1 .Lmy_2a_skipB_208
	v_lshl_add_u64 v[104:105], v[54:55], 0, s[8:9]
	v_add_co_u32_e32 v92, vcc, 0x5770000, v104
	v_lshl_add_u64 v[160:161], v[52:53], 0, s[8:9]
	v_addc_co_u32_e32 v93, vcc, 0, v105, vcc
	v_add_co_u32_e32 v96, vcc, 0x5790000, v104
	s_nop 1
	v_addc_co_u32_e32 v97, vcc, 0, v105, vcc
	v_add_co_u32_e32 v106, vcc, 0x57b0000, v104
	global_load_dwordx4 v[92:95], v[92:93], off offset:256
	s_nop 0
	global_load_dwordx4 v[96:99], v[96:97], off offset:256
	v_addc_co_u32_e32 v107, vcc, 0, v105, vcc
	v_add_co_u32_e32 v108, vcc, 0x57d0000, v104
	s_nop 1
	v_addc_co_u32_e32 v109, vcc, 0, v105, vcc
	global_load_dwordx4 v[104:107], v[106:107], off offset:256
	s_nop 0
	global_load_dwordx4 v[108:111], v[108:109], off offset:256
	s_nop 0
	global_load_dwordx4 v[160:163], v[160:161], off offset:128

; __device__ __forceinline__ f32x4 mfma16(bf16x8 a, bf16x8 b, f32x4 c) { return __builtin_amdgcn_mfma_f32_16x16x32_bf16(a, b, c, 0, 0, 0); }
; template <int NT, bool LOWREG = false>
; __device__ __forceinline__ void gemm_mainloop(const bh* __restrict__ A, long lda, const bh* __restrict__ B, long ldb, int K,
;                                               char* lds, f32x4 (&acc)[4][NT]) {
;     ...
;     const char* sb = lds + (kt & 1) * STAGE;
;     const char* a_base = sb + (wr * 64 + fr) * LROW + fq * 16;
;     const char* b_base = sb + A_BYTES + (wc * (16 * NT) + fr) * LROW + fq * 16;
; #pragma unroll
;     for (int ks = 0; ks < 2; ++ks) {
;       if constexpr (LOWREG) {
;         bf16x8 bfr[NT];
; #pragma unroll
;         for (int n = 0; n < NT; ++n) bfr[n] = *reinterpret_cast<const bf16x8*>(b_base + n * 16 * LROW + ks * 64);
; #pragma unroll
;         for (int mp = 0; mp < 2; ++mp) {
;           bf16x8 af[2];
; #pragma unroll
;           for (int m = 0; m < 2; ++m) af[m] = *reinterpret_cast<const bf16x8*>(a_base + (mp * 2 + m) * 16 * LROW + ks * 64);
;           __builtin_amdgcn_s_setprio(1);
; #pragma unroll
;           for (int m = 0; m < 2; ++m)
; #pragma unroll
;             for (int n = 0; n < NT; ++n) acc[mp * 2 + m][n] = mfma16(af[m], bfr[n], acc[mp * 2 + m][n]);
;           __builtin_amdgcn_s_setprio(0);
;         }
;       } else {
;       bf16x8 af[4], bfr[NT];
; #pragma unroll
;       for (int m = 0; m < 4; ++m) af[m] = *reinterpret_cast<const bf16x8*>(a_base + m * 16 * LROW + ks * 64);
; #pragma unroll
;       for (int n = 0; n < NT; ++n) bfr[n] = *reinterpret_cast<const bf16x8*>(b_base + n * 16 * LROW + ks * 64);
;       __builtin_amdgcn_s_setprio(1);
; #pragma unroll
;       for (int m = 0; m < 4; ++m)
; #pragma unroll
;         for (int n = 0; n < NT; ++n) acc[m][n] = mfma16(af[m], bfr[n], acc[m][n]);
;       __builtin_amdgcn_s_setprio(0);
;       }
;     }
;     if (more) {
;       char* wb = lds + ((kt + 1) & 1) * STAGE;
; #pragma unroll
;       for (int i = 0; i < 4; ++i) *reinterpret_cast<bf16x8*>(wb + (srow + 64 * i) * LROW + scol * 2) = ra[i];
; #pragma unroll
;       for (int i = 0; i < NB; ++i) *reinterpret_cast<bf16x8*>(wb + A_BYTES + (srow + 64 * i) * LROW + scol * 2) = rb[i];
;     }
;     __syncthreads();
.LBB0_209:
	s_add_i32 s5, s3, 1
	s_bitcmp1_b32 s3, 0
	s_cselect_b32 s3, 0xc800, 0
	s_add_i32 s3, s3, 32
	v_add3_u32 v86, s3, v60, v58
	v_add3_u32 v87, s3, v61, v58
	ds_read_b128 v[62:65], v86
	ds_read_b128 v[66:69], v86 offset:2560
	ds_read_b128 v[70:73], v86 offset:5120
	ds_read_b128 v[74:77], v86 offset:7680
	ds_read_b128 v[78:81], v87 offset:40960
	ds_read_b128 v[82:85], v87 offset:43520
	s_setprio 1
	s_waitcnt lgkmcnt(1)
	v_mfma_f32_16x16x32_bf16 v[48:51], v[62:65], v[78:81], v[48:51]
	s_waitcnt lgkmcnt(0)
	v_mfma_f32_16x16x32_bf16 v[44:47], v[62:65], v[82:85], v[44:47]
	v_mfma_f32_16x16x32_bf16 v[40:43], v[66:69], v[78:81], v[40:43]
	v_mfma_f32_16x16x32_bf16 v[24:27], v[66:69], v[82:85], v[24:27]
	v_mfma_f32_16x16x32_bf16 v[12:15], v[70:73], v[78:81], v[12:15]
	v_mfma_f32_16x16x32_bf16 v[8:11], v[70:73], v[82:85], v[8:11]
	v_mfma_f32_16x16x32_bf16 v[4:7], v[74:77], v[78:81], v[4:7]
	v_mfma_f32_16x16x32_bf16 v[0:3], v[74:77], v[82:85], v[0:3]
	s_setprio 0
	ds_read_b128 v[62:65], v86 offset:64
	ds_read_b128 v[66:69], v86 offset:2624
	ds_read_b128 v[70:73], v86 offset:5184
	ds_read_b128 v[74:77], v86 offset:7744
	ds_read_b128 v[78:81], v87 offset:41024
	ds_read_b128 v[82:85], v87 offset:43584
	s_cmpk_eq_i32 s8, 0x700
	s_cbranch_scc1 .Lmy_2a_tailA_208
	s_bitcmp1_b32 s5, 0
	s_cselect_b32 s3, 0xc800, 0
	s_add_i32 s3, s3, 32
	s_setprio 1
	s_waitcnt lgkmcnt(1)
	v_mfma_f32_16x16x32_bf16 v[48:51], v[62:65], v[78:81], v[48:51]
	s_waitcnt lgkmcnt(0)
	v_mfma_f32_16x16x32_bf16 v[44:47], v[62:65], v[82:85], v[44:47]
	v_mfma_f32_16x16x32_bf16 v[40:43], v[66:69], v[78:81], v[40:43]
	v_add3_u32 v62, s3, v176, v59
	s_waitcnt vmcnt(9)
	ds_write_b128 v62, v[16:19]
	v_mfma_f32_16x16x32_bf16 v[24:27], v[66:69], v[82:85], v[24:27]
	s_waitcnt vmcnt(8)
	ds_write_b128 v62, v[20:23] offset:10240
	v_mfma_f32_16x16x32_bf16 v[12:15], v[70:73], v[78:81], v[12:15]
	s_waitcnt vmcnt(7)
	ds_write_b128 v62, v[28:31] offset:20480
	v_mfma_f32_16x16x32_bf16 v[8:11], v[70:73], v[82:85], v[8:11]
	s_waitcnt vmcnt(6)
	ds_write_b128 v62, v[32:35] offset:30720
	v_mfma_f32_16x16x32_bf16 v[4:7], v[74:77], v[78:81], v[4:7]
	v_add3_u32 v62, s3, v59, v176
	s_waitcnt vmcnt(5)
	ds_write_b128 v62, v[36:39] offset:40960
	v_mfma_f32_16x16x32_bf16 v[0:3], v[74:77], v[82:85], v[0:3]
	s_setprio 0
	s_branch .LBB0_208
.Lmy_2a_tailA_208:
	s_bitcmp1_b32 s5, 0
	s_cselect_b32 s3, 0xc800, 0
	s_add_i32 s3, s3, 32
	s_setprio 1
	s_waitcnt lgkmcnt(1)
	v_mfma_f32_16x16x32_bf16 v[48:51], v[62:65], v[78:81], v[48:51]
	s_waitcnt lgkmcnt(0)
	v_mfma_f32_16x16x32_bf16 v[44:47], v[62:65], v[82:85], v[44:47]
	v_mfma_f32_16x16x32_bf16 v[40:43], v[66:69], v[78:81], v[40:43]
	v_add3_u32 v62, s3, v176, v59
	s_waitcnt vmcnt(4)
	ds_write_b128 v62, v[16:19]
	v_mfma_f32_16x16x32_bf16 v[24:27], v[66:69], v[82:85], v[24:27]
	s_waitcnt vmcnt(3)
	ds_write_b128 v62, v[20:23] offset:10240
	v_mfma_f32_16x16x32_bf16 v[12:15], v[70:73], v[78:81], v[12:15]
	s_waitcnt vmcnt(2)
	ds_write_b128 v62, v[28:31] offset:20480
	v_mfma_f32_16x16x32_bf16 v[8:11], v[70:73], v[82:85], v[8:11]
	s_waitcnt vmcnt(1)
	ds_write_b128 v62, v[32:35] offset:30720
	v_mfma_f32_16x16x32_bf16 v[4:7], v[74:77], v[78:81], v[4:7]
	v_add3_u32 v62, s3, v59, v176
	s_waitcnt vmcnt(0)
	ds_write_b128 v62, v[36:39] offset:40960
	v_mfma_f32_16x16x32_bf16 v[0:3], v[74:77], v[82:85], v[0:3]
	s_setprio 0
	s_branch .LBB0_208
